# lora LDS staging + 8-wave split; cached per-head/per-sequence parameter vectors in P5a/P6/P1; prefetch waits moved after the math
# speedup vs baseline: 1.0387x; 1.0142x over previous
.LBB0_564:
	s_mov_b32 s0, 0x8400
	v_cmp_gt_i32_e32 vcc, s0, v2
	s_and_saveexec_b64 s[6:7], vcc
	s_cbranch_execz .LBB0_587
	v_bfe_u32 v44, v4, 4, 2
	v_ashrrev_i32_e32 v7, 1, v2
	v_and_or_b32 v0, v7, -4, v44
	s_movk_i32 s0, 0x3fff
	v_and_b32_e32 v5, 63, v4
	v_cmp_lt_i32_e32 vcc, s0, v0
	v_add_u32_e32 v1, -1, v0
	s_and_saveexec_b64 s[0:1], vcc
	s_xor_b64 s[0:1], exec, s[0:1]
	v_add_u32_e32 v6, 0xffffc000, v7
	v_lshrrev_b32_e32 v6, 2, v6
	v_add_u32_e32 v6, 0x4200, v6
	v_cmp_gt_u32_e32 vcc, 16, v5
	s_nop 1
	v_cndmask_b32_e32 v6, v1, v6, vcc
	s_andn2_saveexec_b64 s[0:1], s[0:1]
	v_and_b32_e32 v6, 0x7ff, v0
	v_cmp_ne_u32_e32 vcc, 0, v6
	s_nop 1
	v_cndmask_b32_e32 v6, -1, v1, vcc
	s_or_b64 exec, exec, s[0:1]
	v_lshlrev_b32_e32 v1, 2, v5
	v_and_b32_e32 v45, 60, v1
	v_ashrrev_i32_e32 v1, 31, v0
	v_lshlrev_b64 v[10:11], 11, v[0:1]
	v_lshlrev_b32_e32 v1, 6, v2
	s_movk_i32 s34, 0x1c0
	v_and_or_b32 v1, v1, s34, v45
	v_readlane_b32 s0, v250, 21
	v_lshl_add_u64 v[12:13], s[36:37], 0, v[10:11]
	v_lshlrev_b32_e32 v8, 1, v1
	v_mov_b32_e32 v9, 0
	v_readlane_b32 s1, v250, 22
	v_max_i32_e32 v1, 0, v6
	s_movk_i32 s35, 0x1d00
	v_mov_b64_e32 v[6:7], s[22:23]
	v_lshl_add_u64 v[12:13], v[12:13], 0, v[8:9]
	v_lshl_add_u64 v[10:11], s[0:1], 0, v[10:11]
	v_mad_u64_u32 v[14:15], s[0:1], v1, s35, v[6:7]
	v_mad_i64_i32 v[0:1], s[0:1], v0, s35, v[6:7]
	v_lshl_add_u64 v[10:11], v[10:11], 0, v[8:9]
	v_lshl_add_u64 v[14:15], v[14:15], 0, v[8:9]
	v_lshl_add_u64 v[0:1], v[0:1], 0, v[8:9]
	global_load_dwordx2 v[30:31], v[12:13], off
	global_load_dwordx2 v[32:33], v[10:11], off offset:1024
	global_load_dwordx2 v[34:35], v[14:15], off offset:2048
	global_load_dwordx2 v[36:37], v[14:15], off
	global_load_dwordx2 v[28:29], v[14:15], off offset:3072
	global_load_dwordx2 v[38:39], v[0:1], off offset:3072
	global_load_dwordx2 v[40:41], v[0:1], off offset:2048
	global_load_dwordx2 v[42:43], v[0:1], off
	s_mov_b32 s93, -1
	s_mul_i32 s0, s82, s20
	v_and_b32_e32 v0, 1, v4
	s_sub_i32 s76, 0x8400, s0
	v_cmp_eq_u32_e64 s[4:5], 0, v0
	v_add_u32_e32 v0, 8, v3
	s_add_u32 s8, s44, 0x1800
	v_mul_lo_u32 v0, s13, v0
	v_readlane_b32 s0, v250, 12
	s_addc_u32 s9, s45, 0
	v_add_u32_e32 v46, s91, v0
	v_lshl_add_u32 v0, s0, 3, v3
	s_lshl_b32 s0, s83, 3
	v_subrev_u32_e32 v0, s0, v0
	v_add_u32_e32 v0, 8, v0
	v_readlane_b32 s0, v250, 23
	v_mul_lo_u32 v0, s13, v0
	s_add_i32 s0, s20, s0
	s_mov_b32 s72, 1
	s_mov_b32 s73, 0
	v_cmp_gt_u32_e64 s[2:3], 16, v5
	v_add_u32_e32 v47, s91, v0
	v_add_u32_e32 v48, s0, v3
	s_mov_b64 s[52:53], 0
	s_movk_i32 s77, 0x3fff
	v_mov_b32_e32 v49, 0x8400
	s_branch .LBB0_571

.LBB0_575:
	s_mov_b32 s0, 0x8400
	s_mov_b32 s10, 0x83ff
	v_cmp_gt_i32_e64 s[0:1], s0, v50
	v_cmp_lt_i32_e32 vcc, s10, v50
	s_and_saveexec_b64 s[48:49], s[0:1]
	s_cbranch_execz .LBB0_581
	v_ashrrev_i32_e32 v4, 1, v50
	v_and_or_b32 v0, v4, -4, v44
	v_cmp_lt_i32_e64 s[0:1], s77, v0
	v_add_u32_e32 v1, -1, v0
	s_and_saveexec_b64 s[10:11], s[0:1]
	s_xor_b64 s[0:1], exec, s[10:11]
	v_add_u32_e32 v3, 0xffffc000, v4
	v_lshrrev_b32_e32 v3, 2, v3
	v_add_u32_e32 v3, 0x4200, v3
	v_cndmask_b32_e64 v3, v1, v3, s[2:3]
	s_andn2_saveexec_b64 s[10:11], s[0:1]
	v_and_b32_e32 v3, 0x7ff, v0
	v_cmp_ne_u32_e64 s[0:1], 0, v3
	s_nop 1
	v_cndmask_b32_e64 v3, -1, v1, s[0:1]
	s_or_b64 exec, exec, s[10:11]
	v_lshlrev_b32_e32 v1, 6, v50
	v_and_or_b32 v8, v1, s34, v45
	v_mov_b64_e32 v[4:5], s[22:23]
	v_mad_i64_i32 v[6:7], s[0:1], v0, s35, v[4:5]
	v_lshlrev_b32_e32 v8, 1, v8
	v_max_i32_e32 v3, 0, v3
	v_lshl_add_u64 v[6:7], v[6:7], 0, v[8:9]
	v_mad_u64_u32 v[4:5], s[0:1], v3, s35, v[4:5]
	v_ashrrev_i32_e32 v1, 31, v0
	v_lshl_add_u64 v[4:5], v[4:5], 0, v[8:9]
	global_load_dwordx2 v[10:11], v[6:7], off
	global_load_dwordx2 v[14:15], v[4:5], off
	global_load_dwordx2 v[12:13], v[6:7], off offset:2048
	global_load_dwordx2 v[16:17], v[4:5], off offset:2048
	global_load_dwordx2 v[18:19], v[6:7], off offset:3072
	global_load_dwordx2 v[20:21], v[4:5], off offset:3072
	v_readlane_b32 s0, v250, 21
	v_lshlrev_b64 v[0:1], 11, v[0:1]
	v_readlane_b32 s1, v250, 22
	s_nop 1
	v_lshl_add_u64 v[4:5], s[0:1], 0, v[0:1]
	v_lshl_add_u64 v[0:1], s[36:37], 0, v[0:1]
	v_lshl_add_u64 v[4:5], v[4:5], 0, v[8:9]
	v_lshl_add_u64 v[0:1], v[0:1], 0, v[8:9]
	global_load_dwordx2 v[22:23], v[4:5], off offset:1024
	global_load_dwordx2 v[24:25], v[0:1], off
	s_waitcnt vmcnt(8)
	s_branch .Lp5a0_join

.Lp5a0_join:
	s_or_b64 exec, exec, s[48:49]
	v_ashrrev_i32_e32 v3, 1, v2
	s_and_b64 s[0:1], exec, vcc
	v_and_or_b32 v26, v3, -4, v44
	s_or_b64 s[52:53], s[0:1], s[52:53]
	v_cmp_lt_i32_e32 vcc, s77, v26
	v_add_u32_e32 v1, -1, v26
	s_and_saveexec_b64 s[0:1], vcc
	s_xor_b64 s[0:1], exec, s[0:1]
	v_add_u32_e32 v0, 0xffffc000, v3
	v_lshrrev_b32_e32 v0, 2, v0
	v_add_u32_e32 v0, 0x4200, v0
	v_cndmask_b32_e64 v0, v1, v0, s[2:3]
	s_andn2_saveexec_b64 s[0:1], s[0:1]
	v_and_b32_e32 v0, 0x7ff, v26
	v_cmp_ne_u32_e32 vcc, 0, v0
	s_nop 1
	v_cndmask_b32_e32 v0, -1, v1, vcc
	s_or_b64 exec, exec, s[0:1]
	v_lshlrev_b32_e32 v1, 6, v2
	v_and_or_b32 v51, v1, s34, v45
	v_lshlrev_b32_e32 v4, 2, v51
	v_cmp_lt_i32_e32 vcc, -1, v0
	v_readfirstlane_b32 s92, v2
	s_nop 3
	s_and_b32 s92, s92, 7
	s_cmp_eq_u32 s92, s93
	s_cbranch_scc1 .Lp5a0_have
	s_mov_b32 s93, s92
	global_load_dwordx4 v[80:83], v4, s[44:45]
	global_load_dwordx4 v[84:87], v4, s[84:85]
	global_load_dwordx4 v[88:91], v4, s[8:9]
	global_load_dwordx4 v[92:95], v4, s[58:59]
	global_load_dwordx4 v[96:99], v4, s[60:61]
	global_load_dwordx4 v[100:103], v4, s[62:63]
	s_waitcnt vmcnt(0)
.Lp5a0_have:
	v_mov_b32_e32 v52, v80
	v_mov_b32_e32 v53, v81
	v_mov_b32_e32 v54, v82
	v_mov_b32_e32 v55, v83
	v_mov_b32_e32 v56, v84
	v_mov_b32_e32 v57, v85
	v_mov_b32_e32 v58, v86
	v_mov_b32_e32 v59, v87
	v_mov_b32_e32 v60, v88
	v_mov_b32_e32 v61, v89
	v_mov_b32_e32 v62, v90
	v_mov_b32_e32 v63, v91
	v_mov_b32_e32 v64, v92
	v_mov_b32_e32 v65, v93
	v_mov_b32_e32 v66, v94
	v_mov_b32_e32 v67, v95
	v_mov_b32_e32 v0, v96
	v_mov_b32_e32 v1, v97
	v_mov_b32_e32 v2, v98
	v_mov_b32_e32 v3, v99
	v_mov_b32_e32 v4, v100
	v_mov_b32_e32 v5, v101
	v_mov_b32_e32 v6, v102
	v_mov_b32_e32 v7, v103
	s_nop 0
	v_cvt_f32_f16_sdwa v69, v42 dst_sel:DWORD dst_unused:UNUSED_PAD src0_sel:WORD_1
	v_cvt_f32_f16_e32 v68, v42
	v_cvt_f32_f16_sdwa v71, v43 dst_sel:DWORD dst_unused:UNUSED_PAD src0_sel:WORD_1
	v_cvt_f32_f16_e32 v70, v43
	v_cvt_f32_f16_sdwa v43, v40 dst_sel:DWORD dst_unused:UNUSED_PAD src0_sel:WORD_1
	v_cvt_f32_f16_e32 v42, v40
	v_cvt_f32_f16_sdwa v73, v41 dst_sel:DWORD dst_unused:UNUSED_PAD src0_sel:WORD_1
	v_cvt_f32_f16_e32 v72, v41
	v_cvt_f32_f16_sdwa v41, v38 dst_sel:DWORD dst_unused:UNUSED_PAD src0_sel:WORD_1
	v_cvt_f32_f16_e32 v40, v38
	v_cvt_f32_f16_sdwa v75, v39 dst_sel:DWORD dst_unused:UNUSED_PAD src0_sel:WORD_1
	v_cvt_f32_f16_e32 v74, v39
	v_cvt_f32_f16_sdwa v39, v36 dst_sel:DWORD dst_unused:UNUSED_PAD src0_sel:WORD_1
	v_cvt_f32_f16_e32 v38, v36
	v_cvt_f32_f16_sdwa v77, v37 dst_sel:DWORD dst_unused:UNUSED_PAD src0_sel:WORD_1
	v_cvt_f32_f16_e32 v76, v37
	v_cndmask_b32_e64 v8, 0, 1.0, vcc
	v_xor_b32_e32 v36, 0x80000000, v68
	v_xor_b32_e32 v37, 0x80000000, v69
	v_pk_fma_f32 v[36:37], v[38:39], v[8:9], v[36:37] op_sel_hi:[1,0,1]
	v_xor_b32_e32 v38, 0x80000000, v70
	v_xor_b32_e32 v39, 0x80000000, v71
	v_pk_fma_f32 v[38:39], v[76:77], v[8:9], v[38:39] op_sel_hi:[1,0,1]
	s_mov_b32 s0, 0x3c800000
	v_pk_fma_f32 v[52:53], v[52:53], v[36:37], v[68:69]
	v_cvt_f32_f16_sdwa v37, v34 dst_sel:DWORD dst_unused:UNUSED_PAD src0_sel:WORD_1
	v_cvt_f32_f16_e32 v36, v34
	v_pk_fma_f32 v[54:55], v[54:55], v[38:39], v[70:71]
	v_cvt_f32_f16_sdwa v39, v35 dst_sel:DWORD dst_unused:UNUSED_PAD src0_sel:WORD_1
	v_cvt_f32_f16_e32 v38, v35
	v_xor_b32_e32 v34, 0x80000000, v42
	v_xor_b32_e32 v35, 0x80000000, v43
	v_pk_fma_f32 v[36:37], v[36:37], v[8:9], v[34:35] op_sel_hi:[1,0,1]
	v_xor_b32_e32 v34, 0x80000000, v72
	v_xor_b32_e32 v35, 0x80000000, v73
	v_pk_fma_f32 v[34:35], v[38:39], v[8:9], v[34:35] op_sel_hi:[1,0,1]
	v_cvt_f32_f16_sdwa v39, v28 dst_sel:DWORD dst_unused:UNUSED_PAD src0_sel:WORD_1
	v_cvt_f32_f16_e32 v38, v28
	v_pk_fma_f32 v[36:37], v[56:57], v[36:37], v[42:43]
	v_cvt_f32_f16_sdwa v43, v29 dst_sel:DWORD dst_unused:UNUSED_PAD src0_sel:WORD_1
	v_cvt_f32_f16_e32 v42, v29
	v_xor_b32_e32 v28, 0x80000000, v40
	v_xor_b32_e32 v29, 0x80000000, v41
	v_pk_fma_f32 v[38:39], v[38:39], v[8:9], v[28:29] op_sel_hi:[1,0,1]
	v_xor_b32_e32 v28, 0x80000000, v74
	v_xor_b32_e32 v29, 0x80000000, v75
	v_pk_fma_f32 v[28:29], v[42:43], v[8:9], v[28:29] op_sel_hi:[1,0,1]
	v_cvt_f32_f16_sdwa v43, v32 dst_sel:DWORD dst_unused:UNUSED_PAD src0_sel:WORD_1
	v_cvt_f32_f16_e32 v42, v32
	v_cvt_f32_f16_sdwa v57, v33 dst_sel:DWORD dst_unused:UNUSED_PAD src0_sel:WORD_1
	v_cvt_f32_f16_e32 v56, v33
	v_pk_fma_f32 v[38:39], v[60:61], v[38:39], v[40:41]
	v_cvt_f32_f16_sdwa v33, v30 dst_sel:DWORD dst_unused:UNUSED_PAD src0_sel:WORD_1
	v_cvt_f32_f16_e32 v32, v30
	v_cvt_f32_f16_sdwa v41, v31 dst_sel:DWORD dst_unused:UNUSED_PAD src0_sel:WORD_1
	v_cvt_f32_f16_e32 v40, v31
	v_pk_mul_f32 v[30:31], v[56:57], v[54:55]
	v_pk_mul_f32 v[42:43], v[42:43], v[52:53]
	v_pk_mul_f32 v[30:31], v[66:67], v[30:31]
	v_pk_mul_f32 v[42:43], v[64:65], v[42:43]
	v_pk_fma_f32 v[28:29], v[62:63], v[28:29], v[74:75]
	v_pk_mov_b32 v[52:53], v[42:43], v[30:31] op_sel:[1,0]
	v_mov_b32_e32 v43, v31
	v_pk_add_f32 v[30:31], v[52:53], v[42:43]
	v_mov_b32_e32 v43, v32
	v_add_f32_e32 v8, v30, v31
	v_pk_mul_f32 v[30:31], v[32:33], v[32:33]
	v_mov_b32_e32 v53, v40
	v_mov_b32_e32 v42, v30
	v_mov_b32_e32 v30, v31
	v_mov_b32_e32 v31, v33
	v_pk_add_f32 v[30:31], v[42:43], v[30:31]
	v_pk_mul_f32 v[42:43], v[40:41], v[40:41]
	v_add_f32_dpp v8, v8, v8 row_ror:8 row_mask:0xf bank_mask:0xf bound_ctrl:1
	v_mov_b32_e32 v52, v42
	v_mov_b32_e32 v42, v43
	v_mov_b32_e32 v43, v41
	v_pk_add_f32 v[42:43], v[52:53], v[42:43]
	v_add_f32_dpp v8, v8, v8 row_ror:4 row_mask:0xf bank_mask:0xf bound_ctrl:1
	v_pk_add_f32 v[30:31], v[30:31], v[42:43]
	v_mov_b32_e32 v43, 0
	v_mov_b32_e32 v42, 0
	v_add_f32_dpp v8, v8, v8 row_ror:2 row_mask:0xf bank_mask:0xf bound_ctrl:1
	v_mov_b32_dpp v43, v31 row_ror:8 row_mask:0xf bank_mask:0xf
	v_mov_b32_dpp v42, v30 row_ror:8 row_mask:0xf bank_mask:0xf
	v_pk_add_f32 v[30:31], v[30:31], v[42:43]
	v_mov_b32_e32 v43, 0
	v_mov_b32_e32 v42, 0
	v_add_f32_dpp v8, v8, v8 row_ror:1 row_mask:0xf bank_mask:0xf bound_ctrl:1
	v_mov_b32_dpp v43, v31 row_ror:4 row_mask:0xf bank_mask:0xf
	v_mov_b32_dpp v42, v30 row_ror:4 row_mask:0xf bank_mask:0xf
	v_pk_add_f32 v[30:31], v[30:31], v[42:43]
	v_mov_b32_e32 v43, 0
	v_mov_b32_e32 v42, 0
	v_pk_fma_f32 v[34:35], v[58:59], v[34:35], v[72:73]
	v_mov_b32_dpp v43, v31 row_ror:2 row_mask:0xf bank_mask:0xf
	v_mov_b32_dpp v42, v30 row_ror:2 row_mask:0xf bank_mask:0xf
	v_pk_add_f32 v[30:31], v[30:31], v[42:43]
	v_mov_b32_e32 v43, 0
	v_mov_b32_e32 v42, 0
	s_nop 0
	v_mov_b32_dpp v43, v31 row_ror:1 row_mask:0xf bank_mask:0xf
	v_mov_b32_dpp v42, v30 row_ror:1 row_mask:0xf bank_mask:0xf
	v_pk_add_f32 v[30:31], v[30:31], v[42:43]
	s_nop 0
	v_pk_mul_f32 v[30:31], v[30:31], s[0:1] op_sel_hi:[1,0]
	s_mov_b32 s0, 0x800000
	v_fma_f32 v27, -v31, v31, v30
	v_max_f32_e32 v27, 0, v27
	v_add_f32_e32 v27, 0x3a27c5ac, v27
	v_cmp_gt_f32_e32 vcc, s0, v27
	v_mul_f32_e32 v30, 0x4b800000, v27
	v_sub_f32_e32 v33, v33, v31
	v_cndmask_b32_e32 v27, v27, v30, vcc
	v_rsq_f32_e32 v27, v27
	v_sub_f32_e32 v32, v32, v31
	v_sub_f32_e32 v41, v41, v31
	v_sub_f32_e32 v40, v40, v31
	v_mul_f32_e32 v30, 0x45800000, v27
	v_cndmask_b32_e32 v30, v27, v30, vcc
	v_pk_mul_f32 v[40:41], v[40:41], v[30:31] op_sel_hi:[1,0]
	v_pk_mul_f32 v[30:31], v[32:33], v[30:31] op_sel_hi:[1,0]
	v_pk_fma_f32 v[2:3], v[2:3], v[40:41], v[6:7]
	v_pk_fma_f32 v[0:1], v[0:1], v[30:31], v[4:5]
	v_mul_f32_e32 v4, 0xbfb8aa3b, v38
	v_mul_f32_e32 v5, 0xbfb8aa3b, v39
	v_exp_f32_e32 v4, v4
	v_exp_f32_e32 v5, v5
	v_pk_fma_f32 v[0:1], v[36:37], v[8:9], v[0:1] op_sel_hi:[1,0,1]
	v_pk_fma_f32 v[2:3], v[34:35], v[8:9], v[2:3] op_sel_hi:[1,0,1]
	v_add_f32_e32 v4, 1.0, v4
	v_add_f32_e32 v5, 1.0, v5
	v_rcp_f32_e32 v4, v4
	v_rcp_f32_e32 v5, v5
	s_nop 0
	v_pk_mul_f32 v[4:5], v[38:39], v[4:5]
	s_nop 0
	v_pk_mul_f32 v[0:1], v[4:5], v[0:1]
	s_nop 0
	v_cvt_pk_f16_f32 v0, v0, v1
	v_mul_f32_e32 v1, 0xbfb8aa3b, v28
	v_exp_f32_e32 v1, v1
	s_nop 0
	v_add_f32_e32 v1, 1.0, v1
	v_rcp_f32_e32 v4, v1
	v_mul_f32_e32 v1, 0xbfb8aa3b, v29
	v_exp_f32_e32 v1, v1
	s_nop 0
	v_add_f32_e32 v1, 1.0, v1
	v_rcp_f32_e32 v5, v1
	s_nop 0
	v_pk_mul_f32 v[4:5], v[28:29], v[4:5]
	s_nop 0
	v_pk_mul_f32 v[2:3], v[4:5], v[2:3]
	s_nop 0
	v_cvt_pk_f16_f32 v1, v2, v3
	v_mov_b32_e32 v2, 0
	v_mov_b32_e32 v3, 0
	s_nop 0
	v_mov_b32_dpp v2, v0 row_shl:1 row_mask:0xf bank_mask:0xf
	v_mov_b32_dpp v3, v1 row_shl:1 row_mask:0xf bank_mask:0xf
	s_waitcnt vmcnt(0)
	s_and_saveexec_b64 s[0:1], s[4:5]
	s_cbranch_execz .LBB0_570
	v_ashrrev_i32_e32 v27, 31, v26
	v_lshlrev_b64 v[4:5], 11, v[26:27]
	v_lshl_add_u64 v[4:5], s[36:37], 0, v[4:5]
	v_lshlrev_b32_e32 v8, 1, v51
	v_lshl_add_u64 v[4:5], v[4:5], 0, v[8:9]
	global_store_dwordx4 v[4:5], v[0:3], off sc1
	s_nop 1
	s_branch .LBB0_570

.LBB0_1180:
	s_mov_b32 s0, 0x8400
	v_cmp_gt_i32_e32 vcc, s0, v25
	s_and_saveexec_b64 s[6:7], vcc
	s_cbranch_execz .LBB0_1203
	v_bfe_u32 v36, v7, 4, 2
	v_ashrrev_i32_e32 v3, 1, v25
	v_and_or_b32 v0, v3, -4, v36
	s_movk_i32 s0, 0x3fff
	v_and_b32_e32 v8, 63, v7
	v_cmp_lt_i32_e32 vcc, s0, v0
	v_add_u32_e32 v1, -1, v0
	s_and_saveexec_b64 s[0:1], vcc
	s_xor_b64 s[0:1], exec, s[0:1]
	v_add_u32_e32 v2, 0xffffc000, v3
	v_lshrrev_b32_e32 v2, 2, v2
	v_add_u32_e32 v2, 0x4200, v2
	v_cmp_gt_u32_e32 vcc, 16, v8
	s_nop 1
	v_cndmask_b32_e32 v2, v1, v2, vcc
	s_andn2_saveexec_b64 s[0:1], s[0:1]
	v_and_b32_e32 v2, 0x7ff, v0
	v_cmp_ne_u32_e32 vcc, 0, v2
	s_nop 1
	v_cndmask_b32_e32 v2, -1, v1, vcc
	s_or_b64 exec, exec, s[0:1]
	v_lshlrev_b32_e32 v1, 2, v8
	v_and_b32_e32 v37, 60, v1
	v_ashrrev_i32_e32 v1, 31, v0
	v_lshlrev_b64 v[10:11], 11, v[0:1]
	v_lshlrev_b32_e32 v1, 6, v25
	s_movk_i32 s31, 0x1c0
	v_and_or_b32 v1, v1, s31, v37
	v_readlane_b32 s0, v250, 21
	v_lshl_add_u64 v[12:13], s[36:37], 0, v[10:11]
	v_lshlrev_b32_e32 v4, 1, v1
	v_mov_b32_e32 v5, 0
	v_readlane_b32 s1, v250, 22
	v_max_i32_e32 v1, 0, v2
	s_movk_i32 s34, 0x1d00
	v_mov_b64_e32 v[2:3], s[22:23]
	v_lshl_add_u64 v[12:13], v[12:13], 0, v[4:5]
	v_lshl_add_u64 v[10:11], s[0:1], 0, v[10:11]
	v_mad_u64_u32 v[14:15], s[0:1], v1, s34, v[2:3]
	v_mad_i64_i32 v[0:1], s[0:1], v0, s34, v[2:3]
	v_lshl_add_u64 v[10:11], v[10:11], 0, v[4:5]
	v_lshl_add_u64 v[14:15], v[14:15], 0, v[4:5]
	v_lshl_add_u64 v[16:17], v[0:1], 0, v[4:5]
	global_load_dwordx2 v[0:1], v[12:13], off
	global_load_dwordx2 v[2:3], v[10:11], off offset:1024
	global_load_dwordx2 v[26:27], v[14:15], off offset:2048
	global_load_dwordx2 v[28:29], v[14:15], off
	global_load_dwordx2 v[22:23], v[14:15], off offset:3072
	global_load_dwordx2 v[30:31], v[16:17], off offset:3072
	global_load_dwordx2 v[32:33], v[16:17], off offset:2048
	global_load_dwordx2 v[34:35], v[16:17], off
	s_mov_b32 s93, -1
	s_mul_i32 s0, s82, s20
	v_and_b32_e32 v4, 1, v7
	s_sub_i32 s48, 0x8400, s0
	v_cmp_eq_u32_e64 s[4:5], 0, v4
	v_add_u32_e32 v4, 8, v6
	s_add_u32 s8, s44, 0x3a00
	v_mul_lo_u32 v4, s13, v4
	v_readlane_b32 s0, v250, 12
	s_addc_u32 s9, s45, 0
	v_add_u32_e32 v38, s91, v4
	v_lshl_add_u32 v4, s0, 3, v6
	s_lshl_b32 s0, s83, 3
	v_subrev_u32_e32 v4, s0, v4
	v_add_u32_e32 v4, 8, v4
	v_readlane_b32 s0, v250, 23
	v_mul_lo_u32 v4, s13, v4
	s_add_i32 s0, s20, s0
	s_mov_b32 s35, 1
	s_mov_b32 s46, 0
	s_mov_b32 s47, 0x8400
	v_cmp_gt_u32_e64 s[2:3], 16, v8
	v_add_u32_e32 v39, s91, v4
	v_add_u32_e32 v40, s0, v6
	s_mov_b64 s[26:27], 0
	s_mov_b32 s44, 0x83ff
	s_movk_i32 s45, 0x3fff
	s_mov_b32 s30, 0x3c800000
	s_mov_b32 s49, 0x800000
	v_mov_b32_e32 v41, 0x8400
	s_branch .LBB0_1187

.LBB0_1192:
	v_ashrrev_i32_e32 v7, 1, v42
	v_and_or_b32 v14, v7, -4, v36
	v_cmp_lt_i32_e64 s[0:1], s45, v14
	v_add_u32_e32 v4, -1, v14
	s_and_saveexec_b64 s[10:11], s[0:1]
	s_xor_b64 s[0:1], exec, s[10:11]
	v_add_u32_e32 v6, 0xffffc000, v7
	v_lshrrev_b32_e32 v6, 2, v6
	v_add_u32_e32 v6, 0x4200, v6
	v_cndmask_b32_e64 v6, v4, v6, s[2:3]
	s_andn2_saveexec_b64 s[10:11], s[0:1]
	v_and_b32_e32 v6, 0x7ff, v14
	v_cmp_ne_u32_e64 s[0:1], 0, v6
	s_nop 1
	v_cndmask_b32_e64 v6, -1, v4, s[0:1]
	s_or_b64 exec, exec, s[10:11]
	v_mov_b64_e32 v[8:9], s[22:23]
	v_max_i32_e32 v6, 0, v6
	v_mad_i64_i32 v[10:11], s[0:1], v14, s34, v[8:9]
	v_mad_u64_u32 v[6:7], s[0:1], v6, s34, v[8:9]
	v_lshlrev_b32_e32 v4, 6, v42
	v_ashrrev_i32_e32 v15, 31, v14
	v_readlane_b32 s0, v250, 21
	v_and_or_b32 v4, v4, s31, v37
	v_lshlrev_b64 v[14:15], 11, v[14:15]
	v_readlane_b32 s1, v250, 22
	v_lshlrev_b32_e32 v4, 1, v4
	v_lshl_add_u64 v[12:13], v[10:11], 0, v[4:5]
	v_lshl_add_u64 v[18:19], s[0:1], 0, v[14:15]
	v_lshl_add_u64 v[14:15], s[36:37], 0, v[14:15]
	v_lshl_add_u64 v[16:17], v[6:7], 0, v[4:5]
	v_lshl_add_u64 v[18:19], v[18:19], 0, v[4:5]
	v_lshl_add_u64 v[20:21], v[14:15], 0, v[4:5]
	global_load_dwordx2 v[6:7], v[12:13], off
	global_load_dwordx2 v[10:11], v[16:17], off
	global_load_dwordx2 v[8:9], v[12:13], off offset:2048
	s_nop 0
	global_load_dwordx2 v[12:13], v[12:13], off offset:3072
	s_nop 0
	global_load_dwordx2 v[14:15], v[16:17], off offset:2048
	s_nop 0
	global_load_dwordx2 v[16:17], v[16:17], off offset:3072
	s_nop 0
	global_load_dwordx2 v[18:19], v[18:19], off offset:1024
	s_nop 0
	global_load_dwordx2 v[20:21], v[20:21], off
	s_waitcnt vmcnt(8)
	s_branch .Lp5a1_join

.Lp5a1_join:
	s_or_b64 exec, exec, s[38:39]
	v_readfirstlane_b32 s92, v25
	v_ashrrev_i32_e32 v44, 1, v25
	s_and_b64 s[0:1], exec, vcc
	v_and_or_b32 v24, v44, -4, v36
	s_or_b64 s[26:27], s[0:1], s[26:27]
	v_cmp_lt_i32_e32 vcc, s45, v24
	v_add_u32_e32 v4, -1, v24
	s_and_saveexec_b64 s[0:1], vcc
	s_xor_b64 s[0:1], exec, s[0:1]
	v_add_u32_e32 v43, 0xffffc000, v44
	v_lshrrev_b32_e32 v43, 2, v43
	v_add_u32_e32 v43, 0x4200, v43
	v_cndmask_b32_e64 v43, v4, v43, s[2:3]
	s_andn2_saveexec_b64 s[0:1], s[0:1]
	v_and_b32_e32 v43, 0x7ff, v24
	v_cmp_ne_u32_e32 vcc, 0, v43
	s_nop 1
	v_cndmask_b32_e32 v43, -1, v4, vcc
	s_or_b64 exec, exec, s[0:1]
	v_lshlrev_b32_e32 v4, 6, v25
	v_and_or_b32 v4, v4, s31, v37
	v_lshlrev_b32_e32 v25, 2, v4
	s_and_b32 s92, s92, 7
	s_cmp_eq_u32 s92, s93
	s_cbranch_scc1 .Lp5a1_have
	s_mov_b32 s93, s92
	global_load_dwordx4 v[120:123], v25, s[24:25]
	global_load_dwordx4 v[124:127], v25, s[28:29]
	global_load_dwordx4 v[128:131], v25, s[8:9]
	global_load_dwordx4 v[132:135], v25, s[58:59] offset:2048
	global_load_dwordx4 v[136:139], v25, s[60:61] offset:2048
	global_load_dwordx4 v[140:143], v25, s[62:63] offset:2048
	s_waitcnt vmcnt(0)
.Lp5a1_have:
	v_mov_b32_e32 v44, v120
	v_mov_b32_e32 v45, v121
	v_mov_b32_e32 v46, v122
	v_mov_b32_e32 v47, v123
	v_mov_b32_e32 v48, v124
	v_mov_b32_e32 v49, v125
	v_mov_b32_e32 v50, v126
	v_mov_b32_e32 v51, v127
	v_mov_b32_e32 v52, v128
	v_mov_b32_e32 v53, v129
	v_mov_b32_e32 v54, v130
	v_mov_b32_e32 v55, v131
	v_mov_b32_e32 v56, v132
	v_mov_b32_e32 v57, v133
	v_mov_b32_e32 v58, v134
	v_mov_b32_e32 v59, v135
	v_cvt_f32_f16_sdwa v63, v34 dst_sel:DWORD dst_unused:UNUSED_PAD src0_sel:WORD_1
	v_cvt_f32_f16_e32 v62, v34
	v_cvt_f32_f16_sdwa v65, v35 dst_sel:DWORD dst_unused:UNUSED_PAD src0_sel:WORD_1
	v_cvt_f32_f16_e32 v64, v35
	v_cvt_f32_f16_sdwa v35, v32 dst_sel:DWORD dst_unused:UNUSED_PAD src0_sel:WORD_1
	v_cvt_f32_f16_e32 v34, v32
	v_cvt_f32_f16_sdwa v67, v33 dst_sel:DWORD dst_unused:UNUSED_PAD src0_sel:WORD_1
	v_cvt_f32_f16_e32 v66, v33
	v_cvt_f32_f16_sdwa v33, v30 dst_sel:DWORD dst_unused:UNUSED_PAD src0_sel:WORD_1
	v_cvt_f32_f16_e32 v32, v30
	v_cvt_f32_f16_sdwa v69, v31 dst_sel:DWORD dst_unused:UNUSED_PAD src0_sel:WORD_1
	v_cvt_f32_f16_e32 v68, v31
	v_cvt_f32_f16_sdwa v31, v28 dst_sel:DWORD dst_unused:UNUSED_PAD src0_sel:WORD_1
	v_cvt_f32_f16_e32 v30, v28
	v_cvt_f32_f16_sdwa v71, v29 dst_sel:DWORD dst_unused:UNUSED_PAD src0_sel:WORD_1
	v_cvt_f32_f16_e32 v70, v29
	v_cvt_f32_f16_sdwa v73, v26 dst_sel:DWORD dst_unused:UNUSED_PAD src0_sel:WORD_1
	v_cvt_f32_f16_e32 v72, v26
	v_cvt_f32_f16_sdwa v75, v27 dst_sel:DWORD dst_unused:UNUSED_PAD src0_sel:WORD_1
	v_cvt_f32_f16_e32 v74, v27
	v_cvt_f32_f16_sdwa v77, v22 dst_sel:DWORD dst_unused:UNUSED_PAD src0_sel:WORD_1
	v_cvt_f32_f16_e32 v76, v22
	v_cvt_f32_f16_sdwa v79, v23 dst_sel:DWORD dst_unused:UNUSED_PAD src0_sel:WORD_1
	v_cvt_f32_f16_e32 v78, v23
	v_cvt_f32_f16_sdwa v23, v2 dst_sel:DWORD dst_unused:UNUSED_PAD src0_sel:WORD_1
	v_cvt_f32_f16_e32 v22, v2
	v_cvt_f32_f16_sdwa v81, v3 dst_sel:DWORD dst_unused:UNUSED_PAD src0_sel:WORD_1
	v_cvt_f32_f16_e32 v80, v3
	v_cvt_f32_f16_sdwa v83, v0 dst_sel:DWORD dst_unused:UNUSED_PAD src0_sel:WORD_1
	v_cvt_f32_f16_e32 v82, v0
	v_cvt_f32_f16_sdwa v85, v1 dst_sel:DWORD dst_unused:UNUSED_PAD src0_sel:WORD_1
	v_cvt_f32_f16_e32 v84, v1
	v_mov_b32_e32 v0, v136
	v_mov_b32_e32 v1, v137
	v_mov_b32_e32 v2, v138
	v_mov_b32_e32 v3, v139
	v_mov_b32_e32 v26, v140
	v_mov_b32_e32 v27, v141
	v_mov_b32_e32 v28, v142
	v_mov_b32_e32 v29, v143
	v_cmp_lt_i32_e32 vcc, -1, v43
	v_mov_b32_e32 v61, 0
	v_xor_b32_e32 v86, 0x80000000, v62
	v_cndmask_b32_e64 v60, 0, 1.0, vcc
	v_xor_b32_e32 v87, 0x80000000, v63
	v_xor_b32_e32 v88, 0x80000000, v64
	v_xor_b32_e32 v89, 0x80000000, v65
	v_pk_fma_f32 v[30:31], v[30:31], v[60:61], v[86:87] op_sel_hi:[1,0,1]
	v_pk_fma_f32 v[70:71], v[70:71], v[60:61], v[88:89] op_sel_hi:[1,0,1]
	v_pk_mul_f32 v[98:99], v[82:83], v[82:83]
	v_pk_mul_f32 v[104:105], v[84:85], v[84:85]
	v_mov_b32_e32 v101, v82
	v_mov_b32_e32 v103, v83
	v_mov_b32_e32 v107, v84
	v_mov_b32_e32 v109, v85
	v_mov_b32_e32 v100, v98
	v_mov_b32_e32 v102, v99
	v_mov_b32_e32 v106, v104
	v_mov_b32_e32 v108, v105
	v_xor_b32_e32 v90, 0x80000000, v34
	v_xor_b32_e32 v91, 0x80000000, v35
	v_xor_b32_e32 v92, 0x80000000, v66
	v_xor_b32_e32 v93, 0x80000000, v67
	v_xor_b32_e32 v94, 0x80000000, v32
	v_xor_b32_e32 v95, 0x80000000, v33
	v_xor_b32_e32 v96, 0x80000000, v68
	v_xor_b32_e32 v97, 0x80000000, v69
	v_pk_add_f32 v[86:87], v[100:101], v[102:103]
	v_pk_add_f32 v[88:89], v[106:107], v[108:109]
	v_pk_fma_f32 v[72:73], v[72:73], v[60:61], v[90:91] op_sel_hi:[1,0,1]
	v_pk_fma_f32 v[74:75], v[74:75], v[60:61], v[92:93] op_sel_hi:[1,0,1]
	v_pk_fma_f32 v[76:77], v[76:77], v[60:61], v[94:95] op_sel_hi:[1,0,1]
	v_pk_fma_f32 v[78:79], v[78:79], v[60:61], v[96:97] op_sel_hi:[1,0,1]
	v_pk_add_f32 v[86:87], v[86:87], v[88:89]
	v_mov_b32_e32 v60, 0
	v_pk_fma_f32 v[46:47], v[46:47], v[70:71], v[64:65]
	v_pk_fma_f32 v[30:31], v[44:45], v[30:31], v[62:63]
	v_pk_mul_f32 v[46:47], v[80:81], v[46:47]
	v_pk_mul_f32 v[22:23], v[22:23], v[30:31]
	v_pk_mul_f32 v[30:31], v[58:59], v[46:47]
	v_pk_mul_f32 v[22:23], v[56:57], v[22:23]
	v_mov_b32_dpp v61, v87 row_ror:8 row_mask:0xf bank_mask:0xf
	v_pk_mov_b32 v[46:47], v[22:23], v[30:31] op_sel:[1,0]
	v_mov_b32_e32 v23, v31
	v_pk_add_f32 v[22:23], v[46:47], v[22:23]
	v_mov_b32_dpp v60, v86 row_ror:8 row_mask:0xf bank_mask:0xf
	v_add_f32_e32 v22, v22, v23
	v_mov_b32_e32 v31, 0
	v_mov_b32_e32 v30, 0
	v_add_f32_dpp v25, v22, v22 row_ror:8 row_mask:0xf bank_mask:0xf bound_ctrl:1
	v_pk_add_f32 v[22:23], v[86:87], v[60:61]
	v_pk_fma_f32 v[44:45], v[50:51], v[74:75], v[66:67]
	v_pk_fma_f32 v[32:33], v[52:53], v[76:77], v[32:33]
	v_mov_b32_dpp v31, v23 row_ror:4 row_mask:0xf bank_mask:0xf
	v_mov_b32_dpp v30, v22 row_ror:4 row_mask:0xf bank_mask:0xf
	v_pk_add_f32 v[22:23], v[22:23], v[30:31]
	v_mov_b32_e32 v31, 0
	v_mov_b32_e32 v30, 0
	v_pk_fma_f32 v[34:35], v[48:49], v[72:73], v[34:35]
	v_mov_b32_dpp v31, v23 row_ror:2 row_mask:0xf bank_mask:0xf
	v_mov_b32_dpp v30, v22 row_ror:2 row_mask:0xf bank_mask:0xf
	v_pk_add_f32 v[22:23], v[22:23], v[30:31]
	v_mov_b32_e32 v31, 0
	v_mov_b32_e32 v30, 0
	v_pk_fma_f32 v[48:49], v[54:55], v[78:79], v[68:69]
	v_mov_b32_dpp v31, v23 row_ror:1 row_mask:0xf bank_mask:0xf
	v_mov_b32_dpp v30, v22 row_ror:1 row_mask:0xf bank_mask:0xf
	v_pk_add_f32 v[22:23], v[22:23], v[30:31]
	s_nop 0
	v_pk_mul_f32 v[22:23], v[22:23], s[30:31] op_sel_hi:[1,0]
	s_nop 0
	v_fma_f32 v22, -v23, v23, v22
	v_max_f32_e32 v22, 0, v22
	v_add_f32_e32 v22, 0x3a27c5ac, v22
	v_mul_f32_e32 v30, 0x4b800000, v22
	v_cmp_gt_f32_e32 vcc, s49, v22
	v_sub_f32_e32 v51, v85, v23
	v_sub_f32_e32 v50, v84, v23
	v_cndmask_b32_e32 v22, v22, v30, vcc
	v_rsq_f32_e32 v30, v22
	v_sub_f32_e32 v47, v83, v23
	v_add_f32_dpp v22, v25, v25 row_ror:4 row_mask:0xf bank_mask:0xf bound_ctrl:1
	v_sub_f32_e32 v46, v82, v23
	v_mul_f32_e32 v25, 0x45800000, v30
	v_cndmask_b32_e32 v30, v30, v25, vcc
	v_add_f32_dpp v22, v22, v22 row_ror:2 row_mask:0xf bank_mask:0xf bound_ctrl:1
	v_pk_mul_f32 v[50:51], v[50:51], v[30:31] op_sel_hi:[1,0]
	v_mul_f32_e32 v25, 0xbfb8aa3b, v33
	v_add_f32_dpp v22, v22, v22 row_ror:1 row_mask:0xf bank_mask:0xf bound_ctrl:1
	v_pk_fma_f32 v[2:3], v[2:3], v[50:51], v[28:29]
	v_exp_f32_e32 v25, v25
	v_pk_fma_f32 v[2:3], v[44:45], v[22:23], v[2:3] op_sel_hi:[1,0,1]
	v_mul_f32_e32 v23, 0xbfb8aa3b, v32
	v_exp_f32_e32 v23, v23
	v_pk_mul_f32 v[30:31], v[46:47], v[30:31] op_sel_hi:[1,0]
	s_nop 0
	v_pk_fma_f32 v[0:1], v[0:1], v[30:31], v[26:27]
	v_mul_f32_e32 v26, 0xbfb8aa3b, v49
	v_pk_fma_f32 v[0:1], v[34:35], v[22:23], v[0:1] op_sel_hi:[1,0,1]
	v_add_f32_e32 v22, 1.0, v23
	v_add_f32_e32 v23, 1.0, v25
	v_mul_f32_e32 v25, 0xbfb8aa3b, v48
	v_exp_f32_e32 v25, v25
	v_exp_f32_e32 v27, v26
	v_rcp_f32_e32 v22, v22
	v_rcp_f32_e32 v23, v23
	v_add_f32_e32 v25, 1.0, v25
	v_rcp_f32_e32 v26, v25
	v_add_f32_e32 v25, 1.0, v27
	v_rcp_f32_e32 v27, v25
	v_pk_mul_f32 v[22:23], v[32:33], v[22:23]
	s_nop 0
	v_pk_mul_f32 v[0:1], v[22:23], v[0:1]
	v_pk_mul_f32 v[22:23], v[48:49], v[26:27]
	v_cvt_pk_f16_f32 v0, v0, v1
	v_pk_mul_f32 v[2:3], v[22:23], v[2:3]
	s_nop 0
	v_cvt_pk_f16_f32 v1, v2, v3
	v_mov_b32_e32 v2, 0
	v_mov_b32_e32 v3, 0
	s_nop 0
	v_mov_b32_dpp v2, v0 row_shl:1 row_mask:0xf bank_mask:0xf
	v_mov_b32_dpp v3, v1 row_shl:1 row_mask:0xf bank_mask:0xf
	s_waitcnt vmcnt(0)
	s_and_saveexec_b64 s[0:1], s[4:5]
	s_cbranch_execz .LBB0_1186
	v_ashrrev_i32_e32 v25, 31, v24
	v_lshlrev_b64 v[22:23], 11, v[24:25]
	v_lshl_add_u64 v[22:23], s[36:37], 0, v[22:23]
	v_lshlrev_b32_e32 v4, 1, v4
	v_lshl_add_u64 v[22:23], v[22:23], 0, v[4:5]
	global_store_dwordx4 v[22:23], v[0:3], off sc1
	s_nop 1
	s_branch .LBB0_1186

.LBB0_1358:
.LBB0_1359:
	v_readlane_b32 s0, v250, 23
	s_nop 1
	v_add_u32_e32 v48, s0, v8
	v_lshlrev_b32_e32 v48, 3, v48
.LBB0_1360:
	s_movk_i32 s8, 0x4200
	v_cmp_gt_i32_e32 vcc, s8, v48
	s_and_saveexec_b64 s[0:1], vcc
	s_cbranch_execz .LBB0_1369
	s_movk_i32 s9, 0x4000
	v_cmp_gt_i32_e32 vcc, s9, v48
	v_mov_b32_e32 v2, s19
	v_mov_b32_e32 v3, s17
	v_add_u32_e32 v0, 0xffffc000, v48
	v_ashrrev_i32_e32 v49, 31, v48
	v_cndmask_b32_e32 v3, v2, v3, vcc
	v_mov_b32_e32 v2, s18
	v_mov_b32_e32 v4, s16
	v_cndmask_b32_e32 v1, 0, v49, vcc
	v_cndmask_b32_e32 v0, v0, v48, vcc
	v_cndmask_b32_e32 v2, v2, v4, vcc
	v_lshlrev_b32_e32 v4, 2, v154
	v_lshlrev_b64 v[0:1], 12, v[0:1]
	v_and_b32_e32 v10, 0xfc, v4
	v_mov_b32_e32 v33, 0
	v_lshl_add_u64 v[0:1], v[2:3], 0, v[0:1]
	v_lshlrev_b64 v[2:3], 12, v[48:49]
	v_lshlrev_b32_e32 v32, 2, v10
	v_lshl_add_u64 v[2:3], s[74:75], 0, v[2:3]
	v_lshl_add_u64 v[12:13], v[0:1], 0, v[32:33]
	v_lshlrev_b32_e32 v14, 1, v10
	v_mov_b32_e32 v15, v33
	v_lshl_add_u64 v[20:21], v[2:3], 0, v[14:15]
	global_load_dwordx4 v[28:31], v[12:13], off
	global_load_dwordx4 v[16:19], v[12:13], off offset:1024
	global_load_dwordx4 v[4:7], v[12:13], off offset:2048
	global_load_dwordx4 v[0:3], v[12:13], off offset:3072
	global_load_dwordx2 v[90:91], v[20:21], off
	global_load_dwordx2 v[86:87], v[20:21], off offset:512
	global_load_dwordx2 v[74:75], v[20:21], off offset:1024
	global_load_dwordx2 v[70:71], v[20:21], off offset:1536
	global_load_dwordx2 v[88:89], v[20:21], off offset:2048
	global_load_dwordx2 v[84:85], v[20:21], off offset:2560
	global_load_dwordx2 v[72:73], v[20:21], off offset:3072
	global_load_dwordx2 v[68:69], v[20:21], off offset:3584
	global_load_dword v130, v[12:13], off
	global_load_dword v131, v[12:13], off
	global_load_dword v132, v[12:13], off
	global_load_dword v133, v[12:13], off
	s_mov_b32 s93, -1
	v_lshl_add_u64 v[36:37], s[40:41], 0, v[32:33]
	s_mov_b64 s[0:1], 0x1000
	v_lshl_add_u64 v[38:39], v[36:37], 0, s[0:1]
	s_mov_b64 s[0:1], 0x1400
	v_lshl_add_u64 v[40:41], v[36:37], 0, s[0:1]
	s_mov_b64 s[0:1], 0x1800
	v_lshl_add_u64 v[42:43], v[36:37], 0, s[0:1]
	s_mov_b64 s[0:1], 0x1c00
	v_lshl_add_u64 v[44:45], v[36:37], 0, s[0:1]
	v_readlane_b32 s0, v250, 12
	s_mov_b32 s10, 1
	v_lshl_add_u64 v[34:35], s[74:75], 0, v[32:33]
	v_lshl_add_u32 v9, s0, 3, v8
	v_readlane_b32 s0, v250, 13
	s_lshl_b32 s0, s0, 3
	v_lshl_add_u64 v[46:47], s[74:75], 0, v[14:15]
	v_subrev_u32_e32 v9, s0, v9
	v_add_u32_e32 v9, 8, v9
	v_readlane_b32 s0, v250, 23
	v_mul_lo_u32 v9, s13, v9
	s_add_i32 s0, s20, s0
	v_add_u32_e32 v100, s91, v9
	v_add_u32_e32 v101, s0, v8
	s_mov_b32 s11, 0
	s_mov_b64 s[2:3], 0
	s_movk_i32 s12, 0x41ff
	v_mov_b32_e32 v102, 0x358637bd
	s_mov_b32 s13, 0x800000
	s_movk_i32 s14, 0x6000
	v_lshlrev_b32_e32 v32, 2, v10
	s_mov_b64 s[4:5], 0x2000
	s_mov_b64 s[6:7], 0x5000
	s_movk_i32 s15, 0x2000
	s_movk_i32 s22, 0x5000
	v_mov_b32_e32 v103, 0x3a800000
	s_branch .LBB0_1363
.LBB0_1362:
	s_or_b64 exec, exec, s[0:1]
	v_cvt_f32_f16_sdwa v117, v90 dst_sel:DWORD dst_unused:UNUSED_PAD src0_sel:WORD_1
	v_cvt_f32_f16_sdwa v119, v91 dst_sel:DWORD dst_unused:UNUSED_PAD src0_sel:WORD_1
	v_cvt_f32_f16_e32 v118, v91
	v_cvt_f32_f16_sdwa v91, v86 dst_sel:DWORD dst_unused:UNUSED_PAD src0_sel:WORD_1
	v_cvt_f32_f16_e32 v116, v90
	v_cvt_f32_f16_e32 v90, v86
	v_cvt_f32_f16_e32 v92, v87
	v_cvt_f32_f16_sdwa v93, v87 dst_sel:DWORD dst_unused:UNUSED_PAD src0_sel:WORD_1
	v_cvt_f32_f16_sdwa v99, v88 dst_sel:DWORD dst_unused:UNUSED_PAD src0_sel:WORD_1
	v_cvt_f32_f16_sdwa v87, v84 dst_sel:DWORD dst_unused:UNUSED_PAD src0_sel:WORD_1
	v_mov_b32_e32 v78, v91
	v_mov_b32_e32 v79, v117
	v_cvt_f32_f16_e32 v98, v88
	v_cvt_f32_f16_e32 v86, v84
	v_mov_b32_e32 v76, v90
	v_mov_b32_e32 v77, v116
	v_pk_mul_f32 v[78:79], v[78:79], v[78:79]
	v_cvt_f32_f16_e32 v120, v89
	v_cvt_f32_f16_e32 v88, v85
	v_pk_fma_f32 v[76:77], v[76:77], v[76:77], v[78:79]
	v_mov_b32_e32 v78, v92
	v_mov_b32_e32 v79, v118
	v_cvt_f32_f16_sdwa v121, v89 dst_sel:DWORD dst_unused:UNUSED_PAD src0_sel:WORD_1
	v_cvt_f32_f16_sdwa v89, v85 dst_sel:DWORD dst_unused:UNUSED_PAD src0_sel:WORD_1
	v_pk_fma_f32 v[76:77], v[78:79], v[78:79], v[76:77]
	v_mov_b32_e32 v78, v93
	v_mov_b32_e32 v79, v119
	v_pk_fma_f32 v[122:123], v[78:79], v[78:79], v[76:77]
	v_mov_b32_e32 v78, v87
	v_mov_b32_e32 v79, v99
	v_add_u32_e32 v49, 0xffffc000, v48
	v_mov_b32_e32 v76, v86
	v_mov_b32_e32 v77, v98
	v_pk_mul_f32 v[78:79], v[78:79], v[78:79]
	v_lshrrev_b32_e32 v49, 2, v49
	v_pk_fma_f32 v[76:77], v[76:77], v[76:77], v[78:79]
	v_mov_b32_e32 v78, v88
	v_mov_b32_e32 v79, v120
	v_add_u32_e32 v67, 8, v49
	v_pk_fma_f32 v[76:77], v[78:79], v[78:79], v[76:77]
	v_mov_b32_e32 v78, v89
	v_mov_b32_e32 v79, v121
	v_cvt_f32_f16_sdwa v81, v68 dst_sel:DWORD dst_unused:UNUSED_PAD src0_sel:WORD_1
	v_cvt_f32_f16_e32 v80, v68
	v_ashrrev_i32_e32 v68, 11, v48
	v_cmp_gt_i32_e32 vcc, s9, v48
	v_pk_fma_f32 v[124:125], v[78:79], v[78:79], v[76:77]
	v_cvt_f32_f16_sdwa v77, v70 dst_sel:DWORD dst_unused:UNUSED_PAD src0_sel:WORD_1
	v_cvt_f32_f16_e32 v76, v70
	v_cvt_f32_f16_sdwa v79, v71 dst_sel:DWORD dst_unused:UNUSED_PAD src0_sel:WORD_1
	v_cvt_f32_f16_e32 v78, v71
	v_cndmask_b32_e32 v67, v67, v68, vcc
	v_mov_b64_e32 v[70:71], s[58:59]
	v_mad_i64_i32 v[70:71], s[0:1], v67, s14, v[70:71]
	v_lshl_add_u64 v[126:127], v[70:71], 0, v[32:33]
	v_add_co_u32_e32 v112, vcc, s15, v126
	v_cvt_f32_f16_sdwa v95, v74 dst_sel:DWORD dst_unused:UNUSED_PAD src0_sel:WORD_1
	v_cvt_f32_f16_e32 v94, v74
	v_cvt_f32_f16_sdwa v97, v75 dst_sel:DWORD dst_unused:UNUSED_PAD src0_sel:WORD_1
	v_cvt_f32_f16_e32 v96, v75
	v_cvt_f32_f16_sdwa v75, v72 dst_sel:DWORD dst_unused:UNUSED_PAD src0_sel:WORD_1
	v_cvt_f32_f16_e32 v74, v72
	v_cvt_f32_f16_sdwa v85, v73 dst_sel:DWORD dst_unused:UNUSED_PAD src0_sel:WORD_1
	v_cvt_f32_f16_e32 v84, v73
	v_readfirstlane_b32 s92, v67
	s_nop 3
	s_cmp_eq_u32 s92, s93
	s_cbranch_scc1 .Lp6_have
	s_mov_b32 s93, s92
	v_lshl_add_u64 v[224:225], v[126:127], 0, s[4:5]
	v_lshl_add_u64 v[226:227], v[126:127], 0, s[6:7]
	global_load_dwordx4 v[160:163], v[36:37], off
	global_load_dwordx4 v[164:167], v[36:37], off offset:1024
	global_load_dwordx4 v[168:171], v[36:37], off offset:2048
	global_load_dwordx4 v[172:175], v[36:37], off offset:3072
	global_load_dwordx4 v[176:179], v[38:39], off
	global_load_dwordx4 v[180:183], v[40:41], off
	global_load_dwordx4 v[184:187], v[42:43], off
	global_load_dwordx4 v[188:191], v[44:45], off
	global_load_dwordx4 v[192:195], v[224:225], off
	global_load_dwordx4 v[196:199], v[224:225], off offset:1024
	global_load_dwordx4 v[200:203], v[224:225], off offset:2048
	global_load_dwordx4 v[204:207], v[224:225], off offset:3072
	global_load_dwordx4 v[208:211], v[226:227], off
	global_load_dwordx4 v[212:215], v[226:227], off offset:1024
	global_load_dwordx4 v[216:219], v[226:227], off offset:2048
	global_load_dwordx4 v[220:223], v[226:227], off offset:3072
	s_waitcnt vmcnt(0)
.Lp6_have:
	s_nop 1
	v_mov_b32_e32 v70, v160
	v_mov_b32_e32 v71, v161
	v_mov_b32_e32 v72, v162
	v_mov_b32_e32 v73, v163
	v_addc_co_u32_e32 v113, vcc, 0, v127, vcc
	s_nop 1
	v_mov_b32_e32 v104, v192
	v_mov_b32_e32 v105, v193
	v_mov_b32_e32 v106, v194
	v_mov_b32_e32 v107, v195
	s_nop 1
	v_mov_b32_e32 v108, v176
	v_mov_b32_e32 v109, v177
	v_mov_b32_e32 v110, v178
	v_mov_b32_e32 v111, v179
	v_add_co_u32_e32 v112, vcc, s22, v126
	v_mov_b32_e32 v128, v77
	s_nop 0
	v_addc_co_u32_e32 v113, vcc, 0, v127, vcc
	s_nop 1
	v_mov_b32_e32 v112, v208
	v_mov_b32_e32 v113, v209
	v_mov_b32_e32 v114, v210
	v_mov_b32_e32 v115, v211
	v_mov_b32_e32 v129, v95
	v_cvt_f32_f16_sdwa v83, v69 dst_sel:DWORD dst_unused:UNUSED_PAD src0_sel:WORD_1
	v_cvt_f32_f16_e32 v82, v69
	v_mov_b32_e32 v68, v76
	v_mov_b32_e32 v69, v94
	v_pk_mul_f32 v[128:129], v[128:129], v[128:129]
	v_add_f32_e32 v67, v122, v123
	v_pk_fma_f32 v[68:69], v[68:69], v[68:69], v[128:129]
	v_mov_b32_e32 v128, v78
	v_mov_b32_e32 v129, v96
	v_pk_fma_f32 v[68:69], v[128:129], v[128:129], v[68:69]
	v_mov_b32_e32 v128, v79
	v_mov_b32_e32 v129, v97
	v_pk_fma_f32 v[68:69], v[128:129], v[128:129], v[68:69]
	v_mov_b32_e32 v122, v81
	v_add_f32_e32 v67, v69, v67
	v_mov_b32_e32 v123, v75
	v_add_f32_e32 v67, v68, v67
	v_mov_b32_e32 v68, v80
	v_mov_b32_e32 v69, v74
	v_pk_mul_f32 v[122:123], v[122:123], v[122:123]
	v_add_f32_dpp v67, v67, v67 row_ror:8 row_mask:0xf bank_mask:0xf bound_ctrl:1
	v_pk_fma_f32 v[68:69], v[68:69], v[68:69], v[122:123]
	v_mov_b32_e32 v122, v82
	v_mov_b32_e32 v123, v84
	v_pk_fma_f32 v[68:69], v[122:123], v[122:123], v[68:69]
	v_mov_b32_e32 v122, v83
	v_mov_b32_e32 v123, v85
	v_pk_fma_f32 v[68:69], v[122:123], v[122:123], v[68:69]
	v_add_f32_e32 v122, v124, v125
	v_add_f32_dpp v67, v67, v67 row_ror:4 row_mask:0xf bank_mask:0xf bound_ctrl:1
	v_add_f32_e32 v69, v69, v122
	v_add_f32_e32 v68, v68, v69
	v_add_f32_dpp v67, v67, v67 row_ror:2 row_mask:0xf bank_mask:0xf bound_ctrl:1
	v_mov_b32_e32 v69, 0
	v_add_f32_dpp v68, v68, v68 row_ror:8 row_mask:0xf bank_mask:0xf bound_ctrl:1
	v_add_f32_dpp v67, v67, v67 row_ror:1 row_mask:0xf bank_mask:0xf bound_ctrl:1
	v_ashrrev_i32_e32 v49, 31, v48
	v_add_f32_dpp v68, v68, v68 row_ror:4 row_mask:0xf bank_mask:0xf bound_ctrl:1
	v_mov_b32_dpp v69, v67 row_bcast:15 row_mask:0xa bank_mask:0xf
	v_add_f32_e32 v67, v67, v69
	v_mov_b32_e32 v69, 0
	v_add_f32_dpp v68, v68, v68 row_ror:2 row_mask:0xf bank_mask:0xf bound_ctrl:1
	v_lshlrev_b64 v[48:49], 12, v[48:49]
	v_mov_b32_dpp v69, v67 row_bcast:31 row_mask:0xc bank_mask:0xf
	v_add_f32_e32 v67, v67, v69
	v_add_f32_dpp v68, v68, v68 row_ror:1 row_mask:0xf bank_mask:0xf bound_ctrl:1
	v_readlane_b32 s0, v67, 63
	v_lshl_add_u64 v[48:49], v[34:35], 0, v[48:49]
	s_add_i32 s11, s11, s20
	v_fma_f32 v67, s0, v103, v102
	v_mul_f32_e32 v69, 0x4b800000, v67
	v_cmp_gt_f32_e32 vcc, s13, v67
	s_add_i32 s10, s10, 1
	s_nop 0
	v_cndmask_b32_e32 v67, v67, v69, vcc
	v_mov_b32_e32 v69, 0
	v_rsq_f32_e32 v67, v67
	s_nop 0
	v_mov_b32_dpp v69, v68 row_bcast:15 row_mask:0xa bank_mask:0xf
	v_add_f32_e32 v68, v68, v69
	v_mov_b32_e32 v69, 0
	s_nop 1
	v_mov_b32_dpp v69, v68 row_bcast:31 row_mask:0xc bank_mask:0xf
	v_add_f32_e32 v68, v68, v69
	s_nop 0
	v_readlane_b32 s0, v68, 63
	s_nop 1
	v_fma_f32 v68, s0, v103, v102
	v_mul_f32_e32 v69, 0x4b800000, v68
	v_cmp_gt_f32_e64 s[0:1], s13, v68
	s_nop 1
	v_cndmask_b32_e64 v68, v68, v69, s[0:1]
	v_rsq_f32_e32 v68, v68
	v_mul_f32_e32 v69, 0x45800000, v67
	v_cndmask_b32_e32 v122, v67, v69, vcc
	v_pk_mul_f32 v[92:93], v[92:93], v[122:123] op_sel_hi:[1,0]
	v_mul_f32_e32 v67, 0x45800000, v68
	v_cndmask_b32_e64 v124, v68, v67, s[0:1]
	v_pk_mul_f32 v[68:69], v[116:117], v[122:123] op_sel_hi:[1,0]
	v_pk_mul_f32 v[116:117], v[118:119], v[122:123] op_sel_hi:[1,0]
	v_pk_mul_f32 v[68:69], v[70:71], v[68:69]
	v_pk_mul_f32 v[72:73], v[72:73], v[116:117]
	v_pk_fma_f32 v[28:29], v[104:105], v[68:69], v[28:29]
	v_pk_mul_f32 v[68:69], v[120:121], v[124:125] op_sel_hi:[1,0]
	v_pk_mul_f32 v[70:71], v[98:99], v[124:125] op_sel_hi:[1,0]
	v_pk_fma_f32 v[30:31], v[106:107], v[72:73], v[30:31]
	v_pk_mul_f32 v[70:71], v[108:109], v[70:71]
	v_pk_mul_f32 v[68:69], v[110:111], v[68:69]
	v_pk_fma_f32 v[28:29], v[112:113], v[70:71], v[28:29]
	v_pk_fma_f32 v[30:31], v[114:115], v[68:69], v[30:31]
	global_store_dwordx4 v[48:49], v[28:31], off
	s_nop 1
	v_mov_b32_e32 v28, v164
	v_mov_b32_e32 v29, v165
	v_mov_b32_e32 v30, v166
	v_mov_b32_e32 v31, v167
	v_lshl_add_u64 v[72:73], v[126:127], 0, s[4:5]
	s_nop 1
	v_mov_b32_e32 v68, v196
	v_mov_b32_e32 v69, v197
	v_mov_b32_e32 v70, v198
	v_mov_b32_e32 v71, v199
	s_nop 1
	v_mov_b32_e32 v104, v180
	v_mov_b32_e32 v105, v181
	v_mov_b32_e32 v106, v182
	v_mov_b32_e32 v107, v183
	v_lshl_add_u64 v[112:113], v[126:127], 0, s[6:7]
	s_nop 1
	v_mov_b32_e32 v108, v212
	v_mov_b32_e32 v109, v213
	v_mov_b32_e32 v110, v214
	v_mov_b32_e32 v111, v215
	v_pk_mul_f32 v[90:91], v[90:91], v[122:123] op_sel_hi:[1,0]
	v_pk_mul_f32 v[74:75], v[74:75], v[124:125] op_sel_hi:[1,0]
	v_pk_mul_f32 v[84:85], v[84:85], v[124:125] op_sel_hi:[1,0]
	v_pk_mul_f32 v[78:79], v[78:79], v[122:123] op_sel_hi:[1,0]
	v_pk_mul_f32 v[76:77], v[76:77], v[122:123] op_sel_hi:[1,0]
	v_pk_mul_f32 v[80:81], v[80:81], v[124:125] op_sel_hi:[1,0]
	v_pk_mul_f32 v[82:83], v[82:83], v[124:125] op_sel_hi:[1,0]
	v_pk_mul_f32 v[28:29], v[90:91], v[28:29]
	v_pk_mul_f32 v[30:31], v[92:93], v[30:31]
	v_pk_fma_f32 v[16:17], v[28:29], v[68:69], v[16:17]
	v_pk_fma_f32 v[18:19], v[30:31], v[70:71], v[18:19]
	v_pk_mul_f32 v[28:29], v[86:87], v[124:125] op_sel_hi:[1,0]
	v_pk_mul_f32 v[30:31], v[88:89], v[124:125] op_sel_hi:[1,0]
	v_pk_mul_f32 v[28:29], v[104:105], v[28:29]
	v_pk_mul_f32 v[30:31], v[106:107], v[30:31]
	v_pk_fma_f32 v[16:17], v[108:109], v[28:29], v[16:17]
	v_pk_fma_f32 v[18:19], v[110:111], v[30:31], v[18:19]
	global_store_dwordx4 v[48:49], v[16:19], off offset:1024
	s_nop 1
	v_mov_b32_e32 v16, v168
	v_mov_b32_e32 v17, v169
	v_mov_b32_e32 v18, v170
	v_mov_b32_e32 v19, v171
	s_nop 0
	s_nop 1
	v_mov_b32_e32 v28, v184
	v_mov_b32_e32 v29, v185
	v_mov_b32_e32 v30, v186
	v_mov_b32_e32 v31, v187
	s_nop 1
	v_mov_b32_e32 v68, v200
	v_mov_b32_e32 v69, v201
	v_mov_b32_e32 v70, v202
	v_mov_b32_e32 v71, v203
	s_nop 1
	v_mov_b32_e32 v86, v216
	v_mov_b32_e32 v87, v217
	v_mov_b32_e32 v88, v218
	v_mov_b32_e32 v89, v219
	v_pk_mul_f32 v[90:91], v[96:97], v[122:123] op_sel_hi:[1,0]
	v_pk_mul_f32 v[92:93], v[94:95], v[122:123] op_sel_hi:[1,0]
	v_pk_mul_f32 v[18:19], v[90:91], v[18:19]
	v_pk_mul_f32 v[16:17], v[92:93], v[16:17]
	v_pk_mul_f32 v[30:31], v[84:85], v[30:31]
	v_pk_mul_f32 v[28:29], v[74:75], v[28:29]
	v_pk_fma_f32 v[6:7], v[18:19], v[70:71], v[6:7]
	v_pk_fma_f32 v[4:5], v[16:17], v[68:69], v[4:5]
	v_pk_fma_f32 v[6:7], v[30:31], v[88:89], v[6:7]
	v_pk_fma_f32 v[4:5], v[28:29], v[86:87], v[4:5]
	global_store_dwordx4 v[48:49], v[4:7], off offset:2048
	s_nop 1
	v_mov_b32_e32 v92, v172
	v_mov_b32_e32 v93, v173
	v_mov_b32_e32 v94, v174
	v_mov_b32_e32 v95, v175
	s_nop 1
	v_mov_b32_e32 v96, v188
	v_mov_b32_e32 v97, v189
	v_mov_b32_e32 v98, v190
	v_mov_b32_e32 v99, v191
	s_nop 1
	v_mov_b32_e32 v104, v204
	v_mov_b32_e32 v105, v205
	v_mov_b32_e32 v106, v206
	v_mov_b32_e32 v107, v207
	s_nop 1
	v_mov_b32_e32 v108, v220
	v_mov_b32_e32 v109, v221
	v_mov_b32_e32 v110, v222
	v_mov_b32_e32 v111, v223
	s_waitcnt vmcnt(3)
	v_mov_b64_e32 v[30:31], v[10:11]
	v_mov_b64_e32 v[18:19], v[14:15]
	v_mov_b64_e32 v[4:5], v[20:21]
	v_mov_b64_e32 v[68:69], v[54:55]
	v_mov_b64_e32 v[72:73], v[52:53]
	v_mov_b64_e32 v[84:85], v[64:65]
	v_mov_b64_e32 v[88:89], v[62:63]
	v_mov_b64_e32 v[70:71], v[60:61]
	v_mov_b64_e32 v[74:75], v[58:59]
	v_mov_b64_e32 v[86:87], v[56:57]
	v_mov_b64_e32 v[90:91], v[50:51]
	v_mov_b64_e32 v[28:29], v[8:9]
	v_mov_b64_e32 v[16:17], v[12:13]
	v_mov_b64_e32 v[6:7], v[22:23]
	v_pk_mul_f32 v[76:77], v[76:77], v[92:93]
	v_pk_mul_f32 v[78:79], v[78:79], v[94:95]
	v_pk_mul_f32 v[82:83], v[82:83], v[98:99]
	v_pk_mul_f32 v[80:81], v[80:81], v[96:97]
	v_pk_fma_f32 v[78:79], v[78:79], v[106:107], v[2:3]
	v_pk_fma_f32 v[76:77], v[76:77], v[104:105], v[0:1]
	v_mov_b64_e32 v[0:1], v[24:25]
	v_pk_fma_f32 v[76:77], v[80:81], v[108:109], v[76:77]
	v_pk_fma_f32 v[78:79], v[82:83], v[110:111], v[78:79]
	v_mov_b64_e32 v[2:3], v[26:27]
	global_store_dwordx4 v[48:49], v[76:79], off offset:3072
	v_mov_b32_e32 v48, v66
	s_andn2_b64 exec, exec, s[2:3]
	s_cbranch_execz .LBB0_1369

.LBB0_1365:
	s_andn2_b64 vcc, exec, s[0:1]
	s_cbranch_vccnz .LBB0_1367
	v_add_u32_e32 v66, 1, v48
.LBB0_1367:
	v_cmp_lt_i32_e64 s[0:1], s12, v66
	v_cmp_gt_i32_e32 vcc, s8, v66
	s_or_b64 s[2:3], s[0:1], s[2:3]
	s_and_saveexec_b64 s[0:1], vcc
	s_cbranch_execz .Lp6_skip
	v_add_u32_e32 v8, 0xffffc000, v66
	v_ashrrev_i32_e32 v67, 31, v66
	v_cmp_gt_i32_e32 vcc, s9, v66
	v_mov_b32_e32 v10, s19
	v_mov_b32_e32 v11, s17
	v_cndmask_b32_e32 v9, 0, v67, vcc
	v_cndmask_b32_e32 v8, v8, v66, vcc
	v_cndmask_b32_e32 v11, v10, v11, vcc
	v_mov_b32_e32 v10, s18
	v_mov_b32_e32 v12, s16
	v_cndmask_b32_e32 v10, v10, v12, vcc
	v_lshlrev_b64 v[8:9], 12, v[8:9]
	v_lshl_add_u64 v[8:9], v[10:11], 0, v[8:9]
	v_lshlrev_b64 v[10:11], 12, v[66:67]
	v_lshl_add_u64 v[76:77], v[8:9], 0, v[32:33]
	v_lshl_add_u64 v[78:79], v[46:47], 0, v[10:11]
	global_load_dwordx4 v[8:11], v[76:77], off
	global_load_dwordx4 v[12:15], v[76:77], off offset:1024
	global_load_dwordx4 v[20:23], v[76:77], off offset:2048
	global_load_dwordx4 v[24:27], v[76:77], off offset:3072
	global_load_dwordx2 v[50:51], v[78:79], off
	global_load_dwordx2 v[56:57], v[78:79], off offset:512
	global_load_dwordx2 v[58:59], v[78:79], off offset:1024
	global_load_dwordx2 v[60:61], v[78:79], off offset:1536
	global_load_dwordx2 v[62:63], v[78:79], off offset:2048
	global_load_dwordx2 v[64:65], v[78:79], off offset:2560
	global_load_dwordx2 v[52:53], v[78:79], off offset:3072
	global_load_dwordx2 v[54:55], v[78:79], off offset:3584
	s_waitcnt vmcnt(16)
	s_branch .LBB0_1362
.Lp6_skip:
	s_waitcnt vmcnt(4)
	s_branch .LBB0_1362
